# v51 + final RMSNorm loop unrolled x2 with next-row prefetch (two register sets)
# speedup vs baseline: 1.0232x; 1.0232x over previous
; DI int tid_fresh() { int t = threadIdx.x; asm volatile("" : "+v"(t)); return t; }
; DI void final_phase(const Params& p) {
;     const int tid = tid_fresh(), lane = tid & 63, wid = tid >> 6;
;     const float* h = (const float*)(p.ws + OFF_H);
;     const float* ss = (const float*)(p.ws + OFF_SS) + 3 * MP;
;     for (int r = blockIdx.x * 8 + wid; r < MR; r += gridDim.x * 8) {
;         const float rstd = rsqrtf(ss[r] * (1.0f / 1024.0f) + EPS);
; #pragma unroll
;         for (int i = 0; i < 4; ++i) {
;             const int c = i * 256 + lane * 4;
;             const f32x4 v = *(const f32x4*)(h + (size_t)r * 1024 + c);
;             const f32x4 g = *(const f32x4*)(p.norm_final + c);
;             *(f32x4*)(p.out + (size_t)r * 1024 + c) = v * rstd * g;
;         }
;     }
.LBB0_1613:
	v_ashrrev_i32_e32 v1, 31, v0
	v_lshl_add_u64 v[10:11], v[0:1], 2, s[6:7]
	global_load_dword v9, v[10:11], off
	v_lshlrev_b64 v[10:11], 12, v[0:1]
	v_lshl_add_u64 v[20:21], v[4:5], 0, v[10:11]
	global_load_dwordx4 v[40:43], v[20:21], off
	global_load_dwordx4 v[44:47], v[20:21], off offset:1024
	global_load_dwordx4 v[48:51], v[20:21], off offset:2048
	global_load_dwordx4 v[52:55], v[20:21], off offset:3072
	v_lshl_add_u64 v[18:19], v[6:7], 0, v[10:11]
	global_load_dword v80, v[2:3], off
	global_load_dword v81, v[2:3], off
	global_load_dword v82, v[2:3], off
	global_load_dword v83, v[2:3], off
.Lfn_x:
	v_add_u32_e32 v0, s92, v0
	v_cmp_lt_i32_e32 vcc, s3, v0
	s_or_b64 s[0:1], vcc, s[0:1]
	s_cbranch_vccnz .Lfn_x_last
	v_ashrrev_i32_e32 v1, 31, v0
	v_lshl_add_u64 v[10:11], v[0:1], 2, s[6:7]
	global_load_dword v56, v[10:11], off
	v_lshlrev_b64 v[10:11], 12, v[0:1]
	v_lshl_add_u64 v[76:77], v[4:5], 0, v[10:11]
	global_load_dwordx4 v[60:63], v[76:77], off
	global_load_dwordx4 v[64:67], v[76:77], off offset:1024
	global_load_dwordx4 v[68:71], v[76:77], off offset:2048
	global_load_dwordx4 v[72:75], v[76:77], off offset:3072
	v_lshl_add_u64 v[78:79], v[6:7], 0, v[10:11]
	s_waitcnt vmcnt(9)
	s_branch .Lfn_x_go
.Lfn_x_last:
	s_waitcnt vmcnt(4)
.Lfn_x_go:
	v_fmamk_f32 v1, v9, 0x3a800000, v8
	v_mul_f32_e32 v9, 0x4b800000, v1
	v_cmp_gt_f32_e32 vcc, s2, v1
	s_nop 1
	v_cndmask_b32_e32 v1, v1, v9, vcc
	v_rsq_f32_e32 v1, v1
	s_nop 0
	v_mul_f32_e32 v9, 0x45800000, v1
	v_cndmask_b32_e32 v22, v1, v9, vcc
	v_pk_mul_f32 v[40:41], v[40:41], v[22:23] op_sel_hi:[1,0]
	v_pk_mul_f32 v[42:43], v[42:43], v[22:23] op_sel_hi:[1,0]
	v_pk_mul_f32 v[40:41], v[24:25], v[40:41]
	v_pk_mul_f32 v[42:43], v[26:27], v[42:43]
	global_store_dwordx4 v[18:19], v[40:43], off
	v_pk_mul_f32 v[44:45], v[44:45], v[22:23] op_sel_hi:[1,0]
	v_pk_mul_f32 v[46:47], v[46:47], v[22:23] op_sel_hi:[1,0]
	v_pk_mul_f32 v[44:45], v[28:29], v[44:45]
	v_pk_mul_f32 v[46:47], v[30:31], v[46:47]
	global_store_dwordx4 v[18:19], v[44:47], off offset:1024
	v_pk_mul_f32 v[48:49], v[48:49], v[22:23] op_sel_hi:[1,0]
	v_pk_mul_f32 v[50:51], v[50:51], v[22:23] op_sel_hi:[1,0]
	v_pk_mul_f32 v[48:49], v[32:33], v[48:49]
	v_pk_mul_f32 v[50:51], v[34:35], v[50:51]
	global_store_dwordx4 v[18:19], v[48:51], off offset:2048
	v_pk_mul_f32 v[52:53], v[52:53], v[22:23] op_sel_hi:[1,0]
	v_pk_mul_f32 v[54:55], v[54:55], v[22:23] op_sel_hi:[1,0]
	v_pk_mul_f32 v[52:53], v[36:37], v[52:53]
	v_pk_mul_f32 v[54:55], v[38:39], v[54:55]
	global_store_dwordx4 v[18:19], v[52:55], off offset:3072
	s_andn2_b64 exec, exec, s[0:1]
	s_cbranch_execz .LBB0_1614
.Lfn_y:
	v_add_u32_e32 v0, s92, v0
	v_cmp_lt_i32_e32 vcc, s3, v0
	s_or_b64 s[0:1], vcc, s[0:1]
	s_cbranch_vccnz .Lfn_y_last
	v_ashrrev_i32_e32 v1, 31, v0
	v_lshl_add_u64 v[10:11], v[0:1], 2, s[6:7]
	global_load_dword v9, v[10:11], off
	v_lshlrev_b64 v[10:11], 12, v[0:1]
	v_lshl_add_u64 v[20:21], v[4:5], 0, v[10:11]
	global_load_dwordx4 v[40:43], v[20:21], off
	global_load_dwordx4 v[44:47], v[20:21], off offset:1024
	global_load_dwordx4 v[48:51], v[20:21], off offset:2048
	global_load_dwordx4 v[52:55], v[20:21], off offset:3072
	v_lshl_add_u64 v[18:19], v[6:7], 0, v[10:11]
	s_waitcnt vmcnt(9)
	s_branch .Lfn_y_go

; DI void final_phase(const Params& p) {
;     ...
;         const float rstd = rsqrtf(ss[r] * (1.0f / 1024.0f) + EPS);
; #pragma unroll
;         for (int i = 0; i < 4; ++i) {
;             const int c = i * 256 + lane * 4;
;             const f32x4 v = *(const f32x4*)(h + (size_t)r * 1024 + c);
;             const f32x4 g = *(const f32x4*)(p.norm_final + c);
;             *(f32x4*)(p.out + (size_t)r * 1024 + c) = v * rstd * g;
;         }
.Lfn_y_go:
	v_fmamk_f32 v1, v56, 0x3a800000, v8
	v_mul_f32_e32 v56, 0x4b800000, v1
	v_cmp_gt_f32_e32 vcc, s2, v1
	s_nop 1
	v_cndmask_b32_e32 v1, v1, v56, vcc
	v_rsq_f32_e32 v1, v1
	s_nop 0
	v_mul_f32_e32 v56, 0x45800000, v1
	v_cndmask_b32_e32 v22, v1, v56, vcc
	v_pk_mul_f32 v[60:61], v[60:61], v[22:23] op_sel_hi:[1,0]
	v_pk_mul_f32 v[62:63], v[62:63], v[22:23] op_sel_hi:[1,0]
	v_pk_mul_f32 v[60:61], v[24:25], v[60:61]
	v_pk_mul_f32 v[62:63], v[26:27], v[62:63]
	global_store_dwordx4 v[78:79], v[60:63], off
	v_pk_mul_f32 v[64:65], v[64:65], v[22:23] op_sel_hi:[1,0]
	v_pk_mul_f32 v[66:67], v[66:67], v[22:23] op_sel_hi:[1,0]
	v_pk_mul_f32 v[64:65], v[28:29], v[64:65]
	v_pk_mul_f32 v[66:67], v[30:31], v[66:67]
	global_store_dwordx4 v[78:79], v[64:67], off offset:1024
	v_pk_mul_f32 v[68:69], v[68:69], v[22:23] op_sel_hi:[1,0]
	v_pk_mul_f32 v[70:71], v[70:71], v[22:23] op_sel_hi:[1,0]
	v_pk_mul_f32 v[68:69], v[32:33], v[68:69]
	v_pk_mul_f32 v[70:71], v[34:35], v[70:71]
	global_store_dwordx4 v[78:79], v[68:71], off offset:2048
	v_pk_mul_f32 v[72:73], v[72:73], v[22:23] op_sel_hi:[1,0]
	v_pk_mul_f32 v[74:75], v[74:75], v[22:23] op_sel_hi:[1,0]
	v_pk_mul_f32 v[72:73], v[36:37], v[72:73]
	v_pk_mul_f32 v[74:75], v[38:39], v[74:75]
	global_store_dwordx4 v[78:79], v[72:75], off offset:3072
	s_andn2_b64 exec, exec, s[0:1]
	s_cbranch_execnz .Lfn_x
